# grid sync replaced by one-to-all flag: workgroup 0 raises the low half of the grid barrier word after zeroing the barrier words, others poll it once, workgroup 0 lowers it at kernel end; first phase t
# speedup vs baseline: 1.0195x; 1.0098x over previous
; #define PG8_LAS __attribute__((address_space(3)))
; __global__ void __launch_bounds__(NT) mega(Args a) {
;     ...
;     if (blockIdx.x == 0) { unsigned* bw = (unsigned*)(a.ws + WS_BAR); for (int i = threadIdx.x; i < XCD_BAR_WORDS; i += NT) bw[i] = 0u; }
;     bf16_t* WinT = (bf16_t*)(a.ws + WS_WIN); bf16_t* WoutT = (bf16_t*)(a.ws + WS_WOUT); bf16_t* WupT = (bf16_t*)(a.ws + WS_WUP); bf16_t* WdownT = (bf16_t*)(a.ws + WS_WDOWN);
;     bf16_t* h1b = (bf16_t*)a.out; bf16_t* proj = (bf16_t*)(a.ws + WS_PROJ); bf16_t* mix = (bf16_t*)(a.ws + WS_MIX); bf16_t* xb = (bf16_t*)(a.ws + WS_XB);
;     bf16_t* uph = (bf16_t*)(a.ws + WS_UPH); bf16_t* act = (bf16_t*)(a.ws + WS_ACT); float* ss2 = (float*)(a.ws + WS_SS2);
;     const unsigned mk = a.mask;
;     if (mk & 1u) { phase_weights(a, (PG8_LAS float*)lds, 0, TW_B, (int)blockIdx.x, (int)gridDim.x); }
;     __syncthreads();
;     if (mk & 2048u) phase_norm1(a, (float*)lds_raw);
;     grid.sync();
.LBB0_9:
	s_or_b64 exec, exec, s[10:11]
	s_waitcnt vmcnt(0)
	s_barrier
	v_cmp_eq_u32_e32 vcc, 0, v152
	s_and_saveexec_b64 s[4:5], vcc
	s_cbranch_execz .Lcga_end
	buffer_wbl2 sc1
	s_waitcnt vmcnt(0)
	s_load_dwordx2 s[8:9], s[2:3], 0x58
	v_mov_b32_e32 v6, 0
	v_mov_b32_e32 v7, 1
	s_waitcnt lgkmcnt(0)
	global_atomic_add v6, v7, s[8:9] offset:32

; __global__ void __launch_bounds__(NT) mega(Args a) {
;     ...
;     __syncthreads();
;     if (mk & 2048u) phase_norm1(a, (float*)lds_raw);
;     grid.sync();
;     XcdBarrier xbar = xcd_barrier_post((unsigned*)(a.ws + WS_BAR), xst);
.LBB0_44:
	v_lshrrev_b32_e32 v1, 20, v0
	v_lshrrev_b32_e32 v0, 10, v0
	v_or_b32_e32 v0, v0, v1
	s_movk_i32 s4, 0x3ff
	v_and_or_b32 v0, v0, s4, v152
	v_cmp_eq_u32_e32 vcc, 0, v0
	s_load_dwordx2 s[6:7], s[2:3], 0x58
	s_waitcnt lgkmcnt(0)
	s_and_saveexec_b64 s[4:5], vcc
	s_cbranch_execz .Lcge_x
	v_mov_b32_e32 v1, 0
	global_load_dword v2, v1, s[6:7] offset:32 sc1
.Lcge_x:
	s_or_b64 exec, exec, s[4:5]
	s_barrier
	s_and_saveexec_b64 s[4:5], vcc
	s_cbranch_execz .LBB0_54
	s_waitcnt vmcnt(0)
.Lcgw_chk:
	v_and_b32_e32 v2, 0xffff, v2
	v_cmp_ne_u32_e32 vcc, 0, v2
	s_cbranch_vccnz .Lcgw_done
	s_sleep 1
	global_load_dword v2, v1, s[6:7] offset:32 sc1
	s_waitcnt vmcnt(0)
	s_branch .Lcgw_chk
.Lcgw_done:
	v_writelane_b32 v252, s82, 59
	v_writelane_b32 v252, s6, 60
	v_writelane_b32 v252, s7, 61

; __global__ void __launch_bounds__(NT) mega(Args a) {
;     ...
;     if (mk & 1024u) phase_final(a);
; }
.LBB0_992:
	s_mov_b64 exec, -1
	v_cmp_eq_u32_e32 vcc, 0, v152
	s_and_saveexec_b64 s[0:1], vcc
	s_cbranch_execz .Lcgr_end
	v_readlane_b32 s4, v252, 59
	v_readlane_b32 s2, v252, 60
	v_readlane_b32 s3, v252, 61
	s_cmp_lg_u32 s4, 0
	s_cbranch_scc1 .Lcgr_end
	v_mov_b32_e32 v0, 0
	v_mov_b32_e32 v1, -1
	s_nop 4
	global_atomic_add v0, v1, s[2:3] offset:32
